# swiglu stores write-through only for units 5+ of a workgroup, write-back for units 1-4
# speedup vs baseline: 1.0025x; 1.0025x over previous
; __device__ __forceinline__ unsigned cvt_pk_bf16(float lo, float hi) { unsigned r; asm volatile("v_cvt_pk_bf16_f32 %0, %1, %2" : "=v"(r) : "v"(lo), "v"(hi)); return r; }
;     __device__ __forceinline__ void operator()(const f32x4 (&acc)[2][2][4][2], const Unit& u, int wr, int wc, int fr, int fq) const {
;     ...
;             for (int m = 0; m < 4; ++m) { bf16_t* rowp = O + (size_t)(row0 + ai * HALF + m * 16) * ldc + col0;
;                 float v[8];
; #pragma unroll
;                 for (int n = 0; n < 2; ++n)
; #pragma unroll
;                     for (int j = 0; j < 4; ++j) { const float g = acc[ai][0][m][n][j], up = acc[ai][1][m][n][j];
;                         v[n * 4 + j] = g * __builtin_amdgcn_rcpf(1.0f + __expf(-g)) * up; }
;                 u32x4 w; w.x = cvt_pk_bf16(v[0], v[1]); w.y = cvt_pk_bf16(v[2], v[3]); w.z = cvt_pk_bf16(v[4], v[5]); w.w = cvt_pk_bf16(v[6], v[7]);
;                 if (NT_ACT) __builtin_nontemporal_store(w, (u32x4*)rowp); else *(u32x4*)rowp = w; }
.LBB0_586:
	v_mov_b32_e32 v150, 0xbfb8aa3b
	v_mov_b32_e32 v151, 0xbfb8aa3b
	v_mov_b32_e32 v152, 1.0
	v_mov_b32_e32 v153, 1.0
	v_pk_mul_f32 v[154:155], v[126:127], v[150:151]
	v_pk_mul_f32 v[156:157], v[128:129], v[150:151]
	v_pk_mul_f32 v[158:159], v[118:119], v[150:151]
	v_pk_mul_f32 v[160:161], v[120:121], v[150:151]
	v_exp_f32_e32 v154, v154
	v_exp_f32_e32 v155, v155
	v_exp_f32_e32 v156, v156
	v_exp_f32_e32 v157, v157
	v_exp_f32_e32 v158, v158
	v_exp_f32_e32 v159, v159
	v_exp_f32_e32 v160, v160
	v_exp_f32_e32 v161, v161
	v_pk_add_f32 v[154:155], v[154:155], v[152:153]
	v_pk_add_f32 v[156:157], v[156:157], v[152:153]
	v_pk_add_f32 v[158:159], v[158:159], v[152:153]
	v_pk_add_f32 v[160:161], v[160:161], v[152:153]
	v_rcp_f32_e32 v154, v154
	v_rcp_f32_e32 v155, v155
	v_rcp_f32_e32 v156, v156
	v_rcp_f32_e32 v157, v157
	v_rcp_f32_e32 v158, v158
	v_rcp_f32_e32 v159, v159
	v_rcp_f32_e32 v160, v160
	v_rcp_f32_e32 v161, v161
	v_pk_mul_f32 v[154:155], v[126:127], v[154:155]
	v_pk_mul_f32 v[156:157], v[128:129], v[156:157]
	v_pk_mul_f32 v[158:159], v[118:119], v[158:159]
	v_pk_mul_f32 v[160:161], v[120:121], v[160:161]
	v_pk_mul_f32 v[162:163], v[154:155], v[122:123]
	v_pk_mul_f32 v[164:165], v[156:157], v[124:125]
	v_pk_mul_f32 v[166:167], v[158:159], v[114:115]
	v_pk_mul_f32 v[168:169], v[160:161], v[116:117]
	v_lshl_or_b32 v146, s51, 7, v143
	v_lshl_add_u32 v145, s52, 8, v141
	v_ashrrev_i32_e32 v147, 31, v146
	v_mov_b64_e32 v[138:139], s[74:75]
	s_movk_i32 s11, 0x2c00
	v_mad_i64_i32 v[148:149], s[20:21], v145, s11, v[138:139]
	s_andn2_b64 vcc, exec, s[14:15]
	s_movk_i32 s25, 0x1600
	s_movk_i32 s24, 0x410
	v_lshlrev_b64 v[114:115], 1, v[146:147]
	v_lshl_add_u64 v[120:121], v[148:149], 0, v[114:115]
	v_cvt_pk_bf16_f32 v116, v162, v163
	v_cvt_pk_bf16_f32 v117, v164, v165
	v_cvt_pk_bf16_f32 v118, v166, v167
	v_cvt_pk_bf16_f32 v119, v168, v169
	s_cmp_lt_u32 s50, 5
	s_cbranch_scc1 .Lsw_plain_1
	global_store_dwordx4 v[120:121], v[116:119], off sc1
	s_branch .Lsw_done_1
.Lsw_plain_1:
	global_store_dwordx4 v[120:121], v[116:119], off
.Lsw_done_1:
	v_pk_mul_f32 v[154:155], v[110:111], v[150:151]
	v_pk_mul_f32 v[156:157], v[112:113], v[150:151]
	v_pk_mul_f32 v[158:159], v[102:103], v[150:151]
	v_pk_mul_f32 v[160:161], v[104:105], v[150:151]
	v_exp_f32_e32 v154, v154
	v_exp_f32_e32 v155, v155
	v_exp_f32_e32 v156, v156
	v_exp_f32_e32 v157, v157
	v_exp_f32_e32 v158, v158
	v_exp_f32_e32 v159, v159
	v_exp_f32_e32 v160, v160
	v_exp_f32_e32 v161, v161
	v_pk_add_f32 v[154:155], v[154:155], v[152:153]
	v_pk_add_f32 v[156:157], v[156:157], v[152:153]
	v_pk_add_f32 v[158:159], v[158:159], v[152:153]
	v_pk_add_f32 v[160:161], v[160:161], v[152:153]
	v_rcp_f32_e32 v154, v154
	v_rcp_f32_e32 v155, v155
	v_rcp_f32_e32 v156, v156
	v_rcp_f32_e32 v157, v157
	v_rcp_f32_e32 v158, v158
	v_rcp_f32_e32 v159, v159
	v_rcp_f32_e32 v160, v160
	v_rcp_f32_e32 v161, v161
	v_pk_mul_f32 v[154:155], v[110:111], v[154:155]
	v_pk_mul_f32 v[156:157], v[112:113], v[156:157]
	v_pk_mul_f32 v[158:159], v[102:103], v[158:159]
	v_pk_mul_f32 v[160:161], v[104:105], v[160:161]
	v_pk_mul_f32 v[162:163], v[154:155], v[106:107]
	v_pk_mul_f32 v[164:165], v[156:157], v[108:109]
	v_pk_mul_f32 v[166:167], v[158:159], v[98:99]
	v_pk_mul_f32 v[168:169], v[160:161], v[100:101]
	v_or_b32_e32 v116, 16, v145
	v_mad_i64_i32 v[116:117], s[20:21], v116, s11, v[138:139]
	v_lshl_add_u64 v[102:103], v[116:117], 0, v[114:115]
	v_cvt_pk_bf16_f32 v98, v162, v163
	v_cvt_pk_bf16_f32 v99, v164, v165
	v_cvt_pk_bf16_f32 v100, v166, v167
	v_cvt_pk_bf16_f32 v101, v168, v169
	s_cmp_lt_u32 s50, 5
	s_cbranch_scc1 .Lsw_plain_2
	global_store_dwordx4 v[102:103], v[98:101], off sc1
	s_branch .Lsw_done_2
.Lsw_plain_2:
	global_store_dwordx4 v[102:103], v[98:101], off
.Lsw_done_2:
	v_pk_mul_f32 v[154:155], v[94:95], v[150:151]
	v_pk_mul_f32 v[156:157], v[96:97], v[150:151]
	v_pk_mul_f32 v[158:159], v[86:87], v[150:151]
	v_pk_mul_f32 v[160:161], v[88:89], v[150:151]
	v_exp_f32_e32 v154, v154
	v_exp_f32_e32 v155, v155
	v_exp_f32_e32 v156, v156
	v_exp_f32_e32 v157, v157
	v_exp_f32_e32 v158, v158
	v_exp_f32_e32 v159, v159
	v_exp_f32_e32 v160, v160
	v_exp_f32_e32 v161, v161
	v_pk_add_f32 v[154:155], v[154:155], v[152:153]
	v_pk_add_f32 v[156:157], v[156:157], v[152:153]
	v_pk_add_f32 v[158:159], v[158:159], v[152:153]
	v_pk_add_f32 v[160:161], v[160:161], v[152:153]
	v_rcp_f32_e32 v154, v154
	v_rcp_f32_e32 v155, v155
	v_rcp_f32_e32 v156, v156
	v_rcp_f32_e32 v157, v157
	v_rcp_f32_e32 v158, v158
	v_rcp_f32_e32 v159, v159
	v_rcp_f32_e32 v160, v160
	v_rcp_f32_e32 v161, v161
	v_pk_mul_f32 v[154:155], v[94:95], v[154:155]
	v_pk_mul_f32 v[156:157], v[96:97], v[156:157]
	v_pk_mul_f32 v[158:159], v[86:87], v[158:159]
	v_pk_mul_f32 v[160:161], v[88:89], v[160:161]
	v_pk_mul_f32 v[162:163], v[154:155], v[90:91]
	v_pk_mul_f32 v[164:165], v[156:157], v[92:93]
	v_pk_mul_f32 v[166:167], v[158:159], v[82:83]
	v_pk_mul_f32 v[168:169], v[160:161], v[84:85]
	v_or_b32_e32 v98, 32, v145
	v_mad_i64_i32 v[98:99], s[20:21], v98, s11, v[138:139]
	v_lshl_add_u64 v[86:87], v[98:99], 0, v[114:115]
	v_cvt_pk_bf16_f32 v82, v162, v163
	v_cvt_pk_bf16_f32 v83, v164, v165
	v_cvt_pk_bf16_f32 v84, v166, v167
	v_cvt_pk_bf16_f32 v85, v168, v169
	s_cmp_lt_u32 s50, 5
	s_cbranch_scc1 .Lsw_plain_3
	global_store_dwordx4 v[86:87], v[82:85], off sc1
	s_branch .Lsw_done_3
.Lsw_plain_3:
	global_store_dwordx4 v[86:87], v[82:85], off
; __device__ __forceinline__ unsigned cvt_pk_bf16(float lo, float hi) { unsigned r; asm volatile("v_cvt_pk_bf16_f32 %0, %1, %2" : "=v"(r) : "v"(lo), "v"(hi)); return r; }
;     __device__ __forceinline__ void operator()(const f32x4 (&acc)[2][2][4][2], const Unit& u, int wr, int wc, int fr, int fq) const {
;     ...
;             for (int m = 0; m < 4; ++m) { bf16_t* rowp = O + (size_t)(row0 + ai * HALF + m * 16) * ldc + col0;
;                 float v[8];
; #pragma unroll
;                 for (int n = 0; n < 2; ++n)
; #pragma unroll
;                     for (int j = 0; j < 4; ++j) { const float g = acc[ai][0][m][n][j], up = acc[ai][1][m][n][j];
;                         v[n * 4 + j] = g * __builtin_amdgcn_rcpf(1.0f + __expf(-g)) * up; }
;                 u32x4 w; w.x = cvt_pk_bf16(v[0], v[1]); w.y = cvt_pk_bf16(v[2], v[3]); w.z = cvt_pk_bf16(v[4], v[5]); w.w = cvt_pk_bf16(v[6], v[7]);
;                 if (NT_ACT) __builtin_nontemporal_store(w, (u32x4*)rowp); else *(u32x4*)rowp = w; }
.Lsw_done_3:
	v_pk_mul_f32 v[154:155], v[78:79], v[150:151]
	v_pk_mul_f32 v[156:157], v[80:81], v[150:151]
	v_pk_mul_f32 v[158:159], v[70:71], v[150:151]
	v_pk_mul_f32 v[160:161], v[72:73], v[150:151]
	v_exp_f32_e32 v154, v154
	v_exp_f32_e32 v155, v155
	v_exp_f32_e32 v156, v156
	v_exp_f32_e32 v157, v157
	v_exp_f32_e32 v158, v158
	v_exp_f32_e32 v159, v159
	v_exp_f32_e32 v160, v160
	v_exp_f32_e32 v161, v161
	v_pk_add_f32 v[154:155], v[154:155], v[152:153]
	v_pk_add_f32 v[156:157], v[156:157], v[152:153]
	v_pk_add_f32 v[158:159], v[158:159], v[152:153]
	v_pk_add_f32 v[160:161], v[160:161], v[152:153]
	v_rcp_f32_e32 v154, v154
	v_rcp_f32_e32 v155, v155
	v_rcp_f32_e32 v156, v156
	v_rcp_f32_e32 v157, v157
	v_rcp_f32_e32 v158, v158
	v_rcp_f32_e32 v159, v159
	v_rcp_f32_e32 v160, v160
	v_rcp_f32_e32 v161, v161
	v_pk_mul_f32 v[154:155], v[78:79], v[154:155]
	v_pk_mul_f32 v[156:157], v[80:81], v[156:157]
	v_pk_mul_f32 v[158:159], v[70:71], v[158:159]
	v_pk_mul_f32 v[160:161], v[72:73], v[160:161]
	v_pk_mul_f32 v[162:163], v[154:155], v[74:75]
	v_pk_mul_f32 v[164:165], v[156:157], v[76:77]
	v_pk_mul_f32 v[166:167], v[158:159], v[66:67]
	v_pk_mul_f32 v[168:169], v[160:161], v[68:69]
	v_or_b32_e32 v82, 48, v145
	v_mad_i64_i32 v[82:83], s[20:21], v82, s11, v[138:139]
	v_lshl_add_u64 v[70:71], v[82:83], 0, v[114:115]
	v_cvt_pk_bf16_f32 v66, v162, v163
	v_cvt_pk_bf16_f32 v67, v164, v165
	v_cvt_pk_bf16_f32 v68, v166, v167
	v_cvt_pk_bf16_f32 v69, v168, v169
	s_cmp_lt_u32 s50, 5
	s_cbranch_scc1 .Lsw_plain_4
	global_store_dwordx4 v[70:71], v[66:69], off sc1
	s_branch .Lsw_done_4
.Lsw_plain_4:
	global_store_dwordx4 v[70:71], v[66:69], off
.Lsw_done_4:
	v_pk_mul_f32 v[154:155], v[62:63], v[150:151]
	v_pk_mul_f32 v[156:157], v[64:65], v[150:151]
	v_pk_mul_f32 v[158:159], v[54:55], v[150:151]
	v_pk_mul_f32 v[160:161], v[56:57], v[150:151]
	v_exp_f32_e32 v154, v154
	v_exp_f32_e32 v155, v155
	v_exp_f32_e32 v156, v156
	v_exp_f32_e32 v157, v157
	v_exp_f32_e32 v158, v158
	v_exp_f32_e32 v159, v159
	v_exp_f32_e32 v160, v160
	v_exp_f32_e32 v161, v161
	v_pk_add_f32 v[154:155], v[154:155], v[152:153]
	v_pk_add_f32 v[156:157], v[156:157], v[152:153]
	v_pk_add_f32 v[158:159], v[158:159], v[152:153]
	v_pk_add_f32 v[160:161], v[160:161], v[152:153]
	v_rcp_f32_e32 v154, v154
	v_rcp_f32_e32 v155, v155
	v_rcp_f32_e32 v156, v156
	v_rcp_f32_e32 v157, v157
	v_rcp_f32_e32 v158, v158
	v_rcp_f32_e32 v159, v159
	v_rcp_f32_e32 v160, v160
	v_rcp_f32_e32 v161, v161
	v_pk_mul_f32 v[154:155], v[62:63], v[154:155]
	v_pk_mul_f32 v[156:157], v[64:65], v[156:157]
	v_pk_mul_f32 v[158:159], v[54:55], v[158:159]
	v_pk_mul_f32 v[160:161], v[56:57], v[160:161]
	v_pk_mul_f32 v[162:163], v[154:155], v[58:59]
	v_pk_mul_f32 v[164:165], v[156:157], v[60:61]
	v_pk_mul_f32 v[166:167], v[158:159], v[50:51]
	v_pk_mul_f32 v[168:169], v[160:161], v[52:53]
	v_add_u32_e32 v66, 0x80, v145
	v_mad_i64_i32 v[66:67], s[20:21], v66, s11, v[138:139]
	v_lshl_add_u64 v[54:55], v[66:67], 0, v[114:115]
	v_cvt_pk_bf16_f32 v50, v162, v163
	v_cvt_pk_bf16_f32 v51, v164, v165
	v_cvt_pk_bf16_f32 v52, v166, v167
	v_cvt_pk_bf16_f32 v53, v168, v169
	s_cmp_lt_u32 s50, 5
	s_cbranch_scc1 .Lsw_plain_5
	global_store_dwordx4 v[54:55], v[50:53], off sc1
	s_branch .Lsw_done_5
.Lsw_plain_5:
	global_store_dwordx4 v[54:55], v[50:53], off
.Lsw_done_5:
	v_pk_mul_f32 v[154:155], v[46:47], v[150:151]
	v_pk_mul_f32 v[156:157], v[48:49], v[150:151]
	v_pk_mul_f32 v[158:159], v[38:39], v[150:151]
	v_pk_mul_f32 v[160:161], v[40:41], v[150:151]
	v_exp_f32_e32 v154, v154
	v_exp_f32_e32 v155, v155
	v_exp_f32_e32 v156, v156
	v_exp_f32_e32 v157, v157
	v_exp_f32_e32 v158, v158
	v_exp_f32_e32 v159, v159
	v_exp_f32_e32 v160, v160
	v_exp_f32_e32 v161, v161
	v_pk_add_f32 v[154:155], v[154:155], v[152:153]
	v_pk_add_f32 v[156:157], v[156:157], v[152:153]
	v_pk_add_f32 v[158:159], v[158:159], v[152:153]
	v_pk_add_f32 v[160:161], v[160:161], v[152:153]
	v_rcp_f32_e32 v154, v154
	v_rcp_f32_e32 v155, v155
	v_rcp_f32_e32 v156, v156
	v_rcp_f32_e32 v157, v157
	v_rcp_f32_e32 v158, v158
	v_rcp_f32_e32 v159, v159
	v_rcp_f32_e32 v160, v160
	v_rcp_f32_e32 v161, v161
	v_pk_mul_f32 v[154:155], v[46:47], v[154:155]
	v_pk_mul_f32 v[156:157], v[48:49], v[156:157]
	v_pk_mul_f32 v[158:159], v[38:39], v[158:159]
	v_pk_mul_f32 v[160:161], v[40:41], v[160:161]
	v_pk_mul_f32 v[162:163], v[154:155], v[42:43]
	v_pk_mul_f32 v[164:165], v[156:157], v[44:45]
	v_pk_mul_f32 v[166:167], v[158:159], v[34:35]
	v_pk_mul_f32 v[168:169], v[160:161], v[36:37]
	v_add_u32_e32 v50, 0x90, v145
	v_mad_i64_i32 v[50:51], s[20:21], v50, s11, v[138:139]
	v_lshl_add_u64 v[38:39], v[50:51], 0, v[114:115]
	v_cvt_pk_bf16_f32 v34, v162, v163
	v_cvt_pk_bf16_f32 v35, v164, v165
	v_cvt_pk_bf16_f32 v36, v166, v167
	v_cvt_pk_bf16_f32 v37, v168, v169
	s_cmp_lt_u32 s50, 5
	s_cbranch_scc1 .Lsw_plain_6
	global_store_dwordx4 v[38:39], v[34:37], off sc1
	s_branch .Lsw_done_6
; __device__ __forceinline__ unsigned cvt_pk_bf16(float lo, float hi) { unsigned r; asm volatile("v_cvt_pk_bf16_f32 %0, %1, %2" : "=v"(r) : "v"(lo), "v"(hi)); return r; }
;     __device__ __forceinline__ void operator()(const f32x4 (&acc)[2][2][4][2], const Unit& u, int wr, int wc, int fr, int fq) const {
;     ...
;             for (int m = 0; m < 4; ++m) { bf16_t* rowp = O + (size_t)(row0 + ai * HALF + m * 16) * ldc + col0;
;                 float v[8];
; #pragma unroll
;                 for (int n = 0; n < 2; ++n)
; #pragma unroll
;                     for (int j = 0; j < 4; ++j) { const float g = acc[ai][0][m][n][j], up = acc[ai][1][m][n][j];
;                         v[n * 4 + j] = g * __builtin_amdgcn_rcpf(1.0f + __expf(-g)) * up; }
;                 u32x4 w; w.x = cvt_pk_bf16(v[0], v[1]); w.y = cvt_pk_bf16(v[2], v[3]); w.z = cvt_pk_bf16(v[4], v[5]); w.w = cvt_pk_bf16(v[6], v[7]);
;                 if (NT_ACT) __builtin_nontemporal_store(w, (u32x4*)rowp); else *(u32x4*)rowp = w; }
.Lsw_plain_6:
	global_store_dwordx4 v[38:39], v[34:37], off
.Lsw_done_6:
	v_pk_mul_f32 v[154:155], v[30:31], v[150:151]
	v_pk_mul_f32 v[156:157], v[32:33], v[150:151]
	v_pk_mul_f32 v[158:159], v[22:23], v[150:151]
	v_pk_mul_f32 v[160:161], v[24:25], v[150:151]
	v_exp_f32_e32 v154, v154
	v_exp_f32_e32 v155, v155
	v_exp_f32_e32 v156, v156
	v_exp_f32_e32 v157, v157
	v_exp_f32_e32 v158, v158
	v_exp_f32_e32 v159, v159
	v_exp_f32_e32 v160, v160
	v_exp_f32_e32 v161, v161
	v_pk_add_f32 v[154:155], v[154:155], v[152:153]
	v_pk_add_f32 v[156:157], v[156:157], v[152:153]
	v_pk_add_f32 v[158:159], v[158:159], v[152:153]
	v_pk_add_f32 v[160:161], v[160:161], v[152:153]
	v_rcp_f32_e32 v154, v154
	v_rcp_f32_e32 v155, v155
	v_rcp_f32_e32 v156, v156
	v_rcp_f32_e32 v157, v157
	v_rcp_f32_e32 v158, v158
	v_rcp_f32_e32 v159, v159
	v_rcp_f32_e32 v160, v160
	v_rcp_f32_e32 v161, v161
	v_pk_mul_f32 v[154:155], v[30:31], v[154:155]
	v_pk_mul_f32 v[156:157], v[32:33], v[156:157]
	v_pk_mul_f32 v[158:159], v[22:23], v[158:159]
	v_pk_mul_f32 v[160:161], v[24:25], v[160:161]
	v_pk_mul_f32 v[162:163], v[154:155], v[26:27]
	v_pk_mul_f32 v[164:165], v[156:157], v[28:29]
	v_pk_mul_f32 v[166:167], v[158:159], v[18:19]
	v_pk_mul_f32 v[168:169], v[160:161], v[20:21]
	v_add_u32_e32 v34, 0xa0, v145
	v_mad_i64_i32 v[34:35], s[20:21], v34, s11, v[138:139]
	v_lshl_add_u64 v[22:23], v[34:35], 0, v[114:115]
	v_cvt_pk_bf16_f32 v18, v162, v163
	v_cvt_pk_bf16_f32 v19, v164, v165
	v_cvt_pk_bf16_f32 v20, v166, v167
	v_cvt_pk_bf16_f32 v21, v168, v169
	s_cmp_lt_u32 s50, 5
	s_cbranch_scc1 .Lsw_plain_7
	global_store_dwordx4 v[22:23], v[18:21], off sc1
	s_branch .Lsw_done_7
.Lsw_plain_7:
	global_store_dwordx4 v[22:23], v[18:21], off
.Lsw_done_7:
	v_pk_mul_f32 v[154:155], v[14:15], v[150:151]
	v_pk_mul_f32 v[156:157], v[16:17], v[150:151]
	v_pk_mul_f32 v[158:159], v[6:7], v[150:151]
	v_pk_mul_f32 v[160:161], v[8:9], v[150:151]
	v_exp_f32_e32 v154, v154
	v_exp_f32_e32 v155, v155
	v_exp_f32_e32 v156, v156
	v_exp_f32_e32 v157, v157
	v_exp_f32_e32 v158, v158
	v_exp_f32_e32 v159, v159
	v_exp_f32_e32 v160, v160
	v_exp_f32_e32 v161, v161
	v_pk_add_f32 v[154:155], v[154:155], v[152:153]
	v_pk_add_f32 v[156:157], v[156:157], v[152:153]
	v_pk_add_f32 v[158:159], v[158:159], v[152:153]
	v_pk_add_f32 v[160:161], v[160:161], v[152:153]
	v_rcp_f32_e32 v154, v154
	v_rcp_f32_e32 v155, v155
	v_rcp_f32_e32 v156, v156
	v_rcp_f32_e32 v157, v157
	v_rcp_f32_e32 v158, v158
	v_rcp_f32_e32 v159, v159
	v_rcp_f32_e32 v160, v160
	v_rcp_f32_e32 v161, v161
	v_pk_mul_f32 v[154:155], v[14:15], v[154:155]
	v_pk_mul_f32 v[156:157], v[16:17], v[156:157]
	v_pk_mul_f32 v[158:159], v[6:7], v[158:159]
	v_pk_mul_f32 v[160:161], v[8:9], v[160:161]
	v_pk_mul_f32 v[162:163], v[154:155], v[10:11]
	v_pk_mul_f32 v[164:165], v[156:157], v[12:13]
	v_pk_mul_f32 v[166:167], v[158:159], v[2:3]
	v_pk_mul_f32 v[168:169], v[160:161], v[4:5]
	v_add_u32_e32 v18, 0xb0, v145
	v_mad_i64_i32 v[18:19], s[20:21], v18, s11, v[138:139]
	s_mov_b64 s[20:21], -1
	v_lshl_add_u64 v[6:7], v[18:19], 0, v[114:115]
	v_cvt_pk_bf16_f32 v2, v162, v163
	v_cvt_pk_bf16_f32 v3, v164, v165
	v_cvt_pk_bf16_f32 v4, v166, v167
	v_cvt_pk_bf16_f32 v5, v168, v169
	s_cmp_lt_u32 s50, 5
	s_cbranch_scc1 .Lsw_plain_8
	global_store_dwordx4 v[6:7], v[2:5], off sc1
	s_branch .Lsw_done_8
.Lsw_plain_8:
	global_store_dwordx4 v[6:7], v[2:5], off
.Lsw_done_8:
	s_cbranch_vccnz .LBB0_557
	s_andn2_b64 vcc, exec, s[6:7]
	s_cbranch_vccnz .LBB0_556
	s_barrier
	s_branch .LBB0_556
